# attention unit prologue: V tile-0 and second K half-tile loads issued right after the first K load (before the Q norm math) instead of just before their LDS writes
# baseline (speedup 1.0000x reference)
; __device__ __forceinline__ float sum32(float v) { const auto rr = __builtin_amdgcn_permlane32_swap(__float_as_uint(v), __float_as_uint(v), false, false); return __uint_as_float(rr[0]) + __uint_as_float(rr[1]); }
; __device__ __forceinline__ void attn_unit(int bh, int qb, const bf16_t* QKV, const bf16_t* KF, const float* cstab, const float* qg, bf16_t* MIX, LAS unsigned char* lds) {
;     ...
;     const int b = bh >> 3, h = bh & 7, q0 = qb * 256, qw = q0 + 32 * wid, q = qw + r32;
;     bf16x8 qf[6];
;     {
;         const bf16_t* Qp = QKV + (size_t)(b * SEQ + q) * 1792 + h * 96 + 8 * hi;
;         const float* cs = cstab + (size_t)(b * SEQ + q) * 32 + 8 * hi;
;         u32x4 raw[6];
; #pragma unroll
;         for (int d0 = 0; d0 < 6; ++d0) raw[d0] = *(const u32x4*)(Qp + 16 * d0);
;         float ss = 0.f;
; #pragma unroll
;         for (int d0 = 0; d0 < 6; ++d0) { float v[8]; unpack8(raw[d0], v);
; #pragma unroll
;             for (int i = 0; i < 8; ++i) ss += v[i] * v[i]; }
;         ss = pg8::sum32(ss);
;         const float rs = __builtin_amdgcn_rsqf(ss * (1.0f / 96.0f) + EPS) * C2Q;
; #pragma unroll
;         for (int d0 = 0; d0 < 4; ++d0) { float v[8]; unpack8(raw[d0], v);
; #pragma unroll
;             for (int i = 0; i < 8; ++i) v[i] = v[i] * rs * qg[16 * d0 + 8 * hi + i];
;             qf[d0] = __builtin_bit_cast(bf16x8, pack8(v)); }
;         float x1[8], x2[8], o1[8], o2[8]; unpack8(raw[4], x1); unpack8(raw[5], x2);
; #pragma unroll
;         for (int i = 0; i < 8; ++i) { const float y1 = x1[i] * rs * qg[64 + 8 * hi + i], y2 = x2[i] * rs * qg[80 + 8 * hi + i], co = cs[i], si = cs[16 + i];
;             o1[i] = y1 * co - y2 * si; o2[i] = y1 * si + y2 * co; }
;         qf[4] = __builtin_bit_cast(bf16x8, pack8(o1)); qf[5] = __builtin_bit_cast(bf16x8, pack8(o2));
;     }
;     const char* Kg = (const char*)(KF + (size_t)bh * SEQ * 96);
;     const char* Vg = (const char*)(QKV + (size_t)b * SEQ * 1792 + 768 + h * 128 + 64) + (size_t)(tid >> 3) * 3584 + (tid & 7) * 16;
;     const int kofs0 = (tid / 12) * KROW + (tid % 12) * 16, kofs1 = ((tid + 512) / 12) * KROW + ((tid + 512) % 12) * 16, vofs = KBUF + (tid >> 3) * VROW + (tid & 7) * 16;
;     const int vtb = KBUF + (4 * hi + ((lane & 15) >> 2)) * VROW + (16 * ((lane >> 4) & 1) + 4 * (lane & 3)) * 2;
;     const int NT = 4 * (qb + 1);
;     u32x4 kr0, kr1 = {0u, 0u, 0u, 0u}, vr;
.LBB0_1037:
	v_mov_b32_e32 v143, v228
	s_and_b32 s29, s27, 7
	s_xor_b32 s23, s29, 15
	v_readfirstlane_b32 s2, v143
	s_ashr_i32 s39, s2, 6
	s_lshl_b32 s22, s23, 8
	s_lshl_b32 s37, s39, 5
	s_ashr_i32 s4, s27, 3
	v_and_b32_e32 v138, 31, v143
	s_ashr_i32 s2, s27, 6
	s_add_i32 s37, s37, s22
	s_and_b32 s36, s4, 7
	v_or_b32_e32 v139, s37, v138
	s_lshl_b32 s28, s2, 12
	s_waitcnt vmcnt(5)
	v_add_u32_e32 v24, s28, v139
	v_mov_b64_e32 v[0:1], s[80:81]
	s_mul_i32 s5, s36, 0x60
	v_bfe_u32 v144, v143, 5, 1
	v_mad_i64_i32 v[0:1], s[6:7], v24, s85, v[0:1]
	s_lshl_b32 s78, s5, 1
	v_lshl_add_u64 v[0:1], v[0:1], 0, s[78:79]
	v_lshlrev_b32_e32 v102, 4, v144
	v_mov_b32_e32 v103, v65
	v_lshl_add_u64 v[0:1], v[0:1], 0, v[102:103]
	global_load_dwordx4 v[56:59], v[0:1], off offset:128
	global_load_dwordx4 v[60:63], v[0:1], off offset:160
	global_load_dwordx4 v[66:69], v[0:1], off offset:96
	global_load_dwordx4 v[70:73], v[0:1], off offset:64
	global_load_dwordx4 v[74:77], v[0:1], off offset:32
	global_load_dwordx4 v[108:111], v[0:1], off
	v_and_b32_e32 v64, 32, v143
	global_load_dwordx4 v[0:3], v64, s[0:1] offset:272
	global_load_dwordx4 v[12:15], v64, s[0:1] offset:256
	global_load_dwordx4 v[4:7], v64, s[0:1] offset:336
	global_load_dwordx4 v[8:11], v64, s[0:1] offset:320
	global_load_dwordx4 v[16:19], v64, s[0:1] offset:208
	global_load_dwordx4 v[20:23], v64, s[0:1] offset:192
	global_load_dwordx4 v[40:43], v64, s[0:1] offset:144
	global_load_dwordx4 v[44:47], v64, s[0:1] offset:128
	global_load_dwordx4 v[48:51], v64, s[0:1] offset:80
	global_load_dwordx4 v[52:55], v64, s[0:1] offset:64
	v_ashrrev_i32_e32 v25, 31, v24
	v_lshlrev_b64 v[24:25], 7, v[24:25]
	v_lshl_add_u64 v[24:25], s[8:9], 0, v[24:25]
	s_mul_i32 s31, s4, 0xc0000
	v_lshl_add_u64 v[36:37], v[24:25], 0, v[64:65]
	s_mul_hi_i32 s30, s4, 0xc0000
	s_add_u32 s14, s10, s31
	global_load_dwordx4 v[24:27], v[36:37], off offset:16
	global_load_dwordx4 v[32:35], v[36:37], off
	global_load_dwordx4 v[28:31], v[36:37], off offset:80
	s_nop 0
	global_load_dwordx4 v[36:39], v[36:37], off offset:64
	s_addc_u32 s15, s11, s30
	s_movk_i32 s4, 0x100
	v_cmp_gt_i32_e64 s[6:7], s4, v143
	s_waitcnt vmcnt(19)
	v_lshlrev_b32_e32 v96, 16, v59
	v_and_b32_e32 v97, 0xffff0000, v59
	s_waitcnt vmcnt(17)
	v_lshlrev_b32_e32 v90, 16, v69
	v_and_b32_e32 v91, 0xffff0000, v69
	v_lshlrev_b32_e32 v92, 16, v68
	s_waitcnt vmcnt(14)
	v_lshlrev_b32_e32 v132, 16, v108
	v_and_b32_e32 v133, 0xffff0000, v108
	v_lshlrev_b32_e32 v108, 4, v143
	v_lshlrev_b32_e32 v130, 16, v109
	v_and_b32_e32 v131, 0xffff0000, v109
	v_ashrrev_i32_e32 v109, 31, v108
	v_and_b32_e32 v93, 0xffff0000, v68
	v_lshl_add_u64 v[68:69], s[14:15], 0, v[108:109]
	v_lshlrev_b32_e32 v94, 16, v63
	v_and_b32_e32 v95, 0xffff0000, v63
	v_lshlrev_b32_e32 v100, 16, v58
	v_and_b32_e32 v101, 0xffff0000, v58
	v_lshlrev_b32_e32 v98, 16, v62
	v_and_b32_e32 v99, 0xffff0000, v62
	v_lshlrev_b32_e32 v112, 16, v57
	v_and_b32_e32 v113, 0xffff0000, v57
	v_lshlrev_b32_e32 v106, 16, v61
	v_and_b32_e32 v107, 0xffff0000, v61
	v_lshlrev_b32_e32 v116, 16, v56
	v_and_b32_e32 v117, 0xffff0000, v56
	v_lshlrev_b32_e32 v114, 16, v60
	v_and_b32_e32 v115, 0xffff0000, v60
	v_lshlrev_b32_e32 v82, 16, v73
	v_and_b32_e32 v83, 0xffff0000, v73
	v_lshlrev_b32_e32 v84, 16, v72
	v_and_b32_e32 v85, 0xffff0000, v72
	v_lshlrev_b32_e32 v122, 16, v71
	v_and_b32_e32 v123, 0xffff0000, v71
	v_lshlrev_b32_e32 v124, 16, v70
	v_and_b32_e32 v125, 0xffff0000, v70
	global_load_dwordx4 v[56:59], v64, s[0:1] offset:16
	global_load_dwordx4 v[60:63], v64, s[0:1]
	global_load_dwordx4 v[70:73], v[68:69], off
	s_mul_i32 s98, s2, 0xe00000
	s_mul_hi_i32 s99, s2, 0xe00000
	s_add_u32 s98, s80, s98
	s_addc_u32 s99, s81, s99
	s_lshl_b32 s100, s36, 8
	s_add_u32 s98, s98, s100
	s_addc_u32 s99, s99, 0
	v_mov_b64_e32 v[166:167], s[98:99]
	v_ashrrev_i32_e32 v164, 3, v143
	s_nop 0
	v_mad_i64_i32 v[166:167], s[100:101], v164, s85, v[166:167]
	v_and_b32_e32 v164, 0x70, v108
	v_mov_b32_e32 v165, 0
	v_lshl_add_u64 v[166:167], v[166:167], 0, v[164:165]
	global_load_dwordx4 v[156:159], v[166:167], off offset:1664
	v_add_u32_e32 v168, 0x200, v143
	v_lshlrev_b32_e32 v168, 4, v168
	v_mov_b32_e32 v169, 0
	v_lshl_add_u64 v[168:169], s[14:15], 0, v[168:169]
	s_and_saveexec_b64 s[100:101], s[6:7]
	global_load_dwordx4 v[160:163], v[168:169], off
	s_mov_b64 exec, s[100:101]
	v_mul_f32_e32 v64, v133, v133
	v_lshlrev_b32_e32 v118, 16, v67
	v_and_b32_e32 v119, 0xffff0000, v67
	v_lshlrev_b32_e32 v120, 16, v66
	v_and_b32_e32 v121, 0xffff0000, v66
	v_pk_fma_f32 v[66:67], v[132:133], v[132:133], v[64:65] op_sel_hi:[1,1,0]
	v_mul_f32_e32 v64, v131, v131
	v_pk_fma_f32 v[66:67], v[130:131], v[130:131], v[66:67]
	v_lshlrev_b32_e32 v128, 16, v110
	v_and_b32_e32 v129, 0xffff0000, v110
	v_pk_add_f32 v[66:67], v[64:65], v[66:67] op_sel_hi:[0,1]
	v_pk_fma_f32 v[66:67], v[128:129], v[128:129], v[66:67]
	v_mul_f32_e32 v64, v129, v129
	v_lshlrev_b32_e32 v126, 16, v111
	v_and_b32_e32 v127, 0xffff0000, v111
	v_pk_add_f32 v[66:67], v[64:65], v[66:67] op_sel_hi:[0,1]
	v_pk_fma_f32 v[66:67], v[126:127], v[126:127], v[66:67]
	v_mul_f32_e32 v64, v127, v127
; __device__ __forceinline__ float sum32(float v) { const auto rr = __builtin_amdgcn_permlane32_swap(__float_as_uint(v), __float_as_uint(v), false, false); return __uint_as_float(rr[0]) + __uint_as_float(rr[1]); }
; #define LAS __attribute__((address_space(3)))
; #define ATT_LOAD(t) do { kr0 = *(const u32x4*)(Kg + (size_t)(t) * 12288 + tid * 16); if (tid < 256) kr1 = *(const u32x4*)(Kg + (size_t)(t) * 12288 + (tid + 512) * 16); vr = *(const u32x4*)(Vg + (size_t)(t) * (64 * 3584)); } while (0)
; #define ATT_WRITE(bufp) do { *(LAS u32x4*)((bufp) + kofs0) = kr0; if (tid < 256) *(LAS u32x4*)((bufp) + kofs1) = kr1; *(LAS u32x4*)((bufp) + vofs) = vr; } while (0)
; __device__ __forceinline__ void attn_unit(int bh, int qb, const bf16_t* QKV, const bf16_t* KF, const float* cstab, const float* qg, bf16_t* MIX, LAS unsigned char* lds) {
;     ...
;         float ss = 0.f;
; #pragma unroll
;         for (int d0 = 0; d0 < 6; ++d0) { float v[8]; unpack8(raw[d0], v);
; #pragma unroll
;             for (int i = 0; i < 8; ++i) ss += v[i] * v[i]; }
;         ss = pg8::sum32(ss);
;         const float rs = __builtin_amdgcn_rsqf(ss * (1.0f / 96.0f) + EPS) * C2Q;
;     ...
;     const char* Vg = (const char*)(QKV + (size_t)b * SEQ * 1792 + 768 + h * 128 + 64) + (size_t)(tid >> 3) * 3584 + (tid & 7) * 16;
;     const int kofs0 = (tid / 12) * KROW + (tid % 12) * 16, kofs1 = ((tid + 512) / 12) * KROW + ((tid + 512) % 12) * 16, vofs = KBUF + (tid >> 3) * VROW + (tid & 7) * 16;
;     const int vtb = KBUF + (4 * hi + ((lane & 15) >> 2)) * VROW + (16 * ((lane >> 4) & 1) + 4 * (lane & 3)) * 2;
;     const int NT = 4 * (qb + 1);
;     u32x4 kr0, kr1 = {0u, 0u, 0u, 0u}, vr;
;     ...
;     float mrun = 0.f, lrun = 0.f;
;     f32x16 o0, o1, negm;
; #pragma unroll
;     for (int r = 0; r < 16; ++r) { o0[r] = 0.f; o1[r] = 0.f; negm[r] = 0.f; }
;     ATT_LOAD(0); ATT_WRITE(lds);
;     __syncthreads();
;     for (int t = 0; t < NT; ++t) {
;         LAS unsigned char* buf = lds + (t & 1) * BUFB;
;         if (t + 1 < NT) ATT_LOAD(t + 1);
	v_lshlrev_b32_e32 v88, 16, v74
	v_and_b32_e32 v89, 0xffff0000, v74
	v_pk_add_f32 v[66:67], v[64:65], v[66:67] op_sel_hi:[0,1]
	v_pk_fma_f32 v[66:67], v[88:89], v[88:89], v[66:67]
	v_mul_f32_e32 v64, v89, v89
	v_lshlrev_b32_e32 v86, 16, v75
	v_and_b32_e32 v87, 0xffff0000, v75
	v_pk_add_f32 v[66:67], v[64:65], v[66:67] op_sel_hi:[0,1]
	v_pk_fma_f32 v[66:67], v[86:87], v[86:87], v[66:67]
	v_mul_f32_e32 v64, v87, v87
	v_lshlrev_b32_e32 v80, 16, v76
	v_and_b32_e32 v81, 0xffff0000, v76
	v_pk_add_f32 v[66:67], v[64:65], v[66:67] op_sel_hi:[0,1]
	v_pk_fma_f32 v[66:67], v[80:81], v[80:81], v[66:67]
	v_mul_f32_e32 v64, v81, v81
	v_lshlrev_b32_e32 v78, 16, v77
	v_and_b32_e32 v79, 0xffff0000, v77
	v_pk_add_f32 v[66:67], v[64:65], v[66:67] op_sel_hi:[0,1]
	v_pk_fma_f32 v[66:67], v[78:79], v[78:79], v[66:67]
	v_mul_f32_e32 v64, v79, v79
	v_pk_add_f32 v[66:67], v[64:65], v[66:67] op_sel_hi:[0,1]
	v_pk_fma_f32 v[66:67], v[124:125], v[124:125], v[66:67]
	v_mul_f32_e32 v64, v125, v125
	v_pk_add_f32 v[66:67], v[64:65], v[66:67] op_sel_hi:[0,1]
	v_pk_fma_f32 v[66:67], v[122:123], v[122:123], v[66:67]
	v_mul_f32_e32 v64, v123, v123
	v_pk_add_f32 v[66:67], v[64:65], v[66:67] op_sel_hi:[0,1]
	v_pk_fma_f32 v[66:67], v[84:85], v[84:85], v[66:67]
	v_mul_f32_e32 v64, v85, v85
	v_pk_add_f32 v[66:67], v[64:65], v[66:67] op_sel_hi:[0,1]
	v_pk_fma_f32 v[66:67], v[82:83], v[82:83], v[66:67]
	v_mul_f32_e32 v64, v83, v83
	v_pk_add_f32 v[66:67], v[64:65], v[66:67] op_sel_hi:[0,1]
	v_pk_fma_f32 v[66:67], v[120:121], v[120:121], v[66:67]
	v_mul_f32_e32 v64, v121, v121
	v_pk_add_f32 v[66:67], v[64:65], v[66:67] op_sel_hi:[0,1]
	v_pk_fma_f32 v[66:67], v[118:119], v[118:119], v[66:67]
	v_mul_f32_e32 v64, v119, v119
	v_pk_add_f32 v[66:67], v[64:65], v[66:67] op_sel_hi:[0,1]
	v_pk_fma_f32 v[66:67], v[92:93], v[92:93], v[66:67]
	v_mul_f32_e32 v64, v93, v93
	v_pk_add_f32 v[66:67], v[64:65], v[66:67] op_sel_hi:[0,1]
	v_pk_fma_f32 v[66:67], v[90:91], v[90:91], v[66:67]
	v_mul_f32_e32 v64, v91, v91
	v_pk_add_f32 v[66:67], v[64:65], v[66:67] op_sel_hi:[0,1]
	v_pk_fma_f32 v[66:67], v[116:117], v[116:117], v[66:67]
	v_mul_f32_e32 v64, v117, v117
	v_pk_add_f32 v[66:67], v[64:65], v[66:67] op_sel_hi:[0,1]
	v_pk_fma_f32 v[66:67], v[112:113], v[112:113], v[66:67]
	v_mul_f32_e32 v64, v113, v113
	v_pk_add_f32 v[66:67], v[64:65], v[66:67] op_sel_hi:[0,1]
	v_pk_fma_f32 v[66:67], v[100:101], v[100:101], v[66:67]
	v_mul_f32_e32 v64, v101, v101
	v_pk_add_f32 v[66:67], v[64:65], v[66:67] op_sel_hi:[0,1]
	v_pk_fma_f32 v[66:67], v[96:97], v[96:97], v[66:67]
	v_mul_f32_e32 v64, v97, v97
	v_pk_add_f32 v[66:67], v[64:65], v[66:67] op_sel_hi:[0,1]
	v_pk_fma_f32 v[66:67], v[114:115], v[114:115], v[66:67]
	v_mul_f32_e32 v64, v115, v115
	v_pk_add_f32 v[66:67], v[64:65], v[66:67] op_sel_hi:[0,1]
	v_pk_fma_f32 v[66:67], v[106:107], v[106:107], v[66:67]
	v_mul_f32_e32 v64, v107, v107
	v_pk_add_f32 v[66:67], v[64:65], v[66:67] op_sel_hi:[0,1]
	v_pk_fma_f32 v[66:67], v[98:99], v[98:99], v[66:67]
	v_mul_f32_e32 v64, v99, v99
	v_pk_add_f32 v[66:67], v[64:65], v[66:67] op_sel_hi:[0,1]
	v_pk_fma_f32 v[66:67], v[94:95], v[94:95], v[66:67]
	v_mul_f32_e32 v64, v95, v95
	v_pk_add_f32 v[134:135], v[64:65], v[66:67] op_sel_hi:[0,1]
	v_add_u32_e32 v74, 0x200, v143
	v_mov_b32_e32 v66, v65
	v_mov_b32_e32 v67, v65
	v_mov_b32_e32 v146, v134
	v_mov_b32_e32 v64, v65
	v_lshlrev_b32_e32 v110, 4, v74
	v_mov_b64_e32 v[68:69], v[66:67]
	v_permlane32_swap_b32_e32 v134, v146
	v_ashrrev_i32_e32 v111, 31, v110
	v_mov_b64_e32 v[66:67], v[64:65]
	s_and_saveexec_b64 s[4:5], s[6:7]
	s_cbranch_execz .LBB0_1039
	v_lshl_add_u64 v[66:67], s[14:15], 0, v[110:111]
.LBB0_1039:
	s_or_b64 exec, exec, s[4:5]
	s_mul_i32 s35, s2, 0xe00000
	s_mul_hi_i32 s34, s2, 0xe00000
	s_add_u32 s2, s80, s35
	s_addc_u32 s4, s81, s34
	s_lshl_b32 s5, s36, 8
	s_add_u32 s18, s2, s5
	s_mov_b32 s2, 0x2aaaaaab
	v_mul_hi_i32 v75, v143, s2
	v_lshrrev_b32_e32 v76, 31, v75
	v_lshrrev_b32_e32 v75, 1, v75
	v_add_u32_e32 v75, v75, v76
	v_mul_hi_i32 v76, v74, s2
	s_addc_u32 s19, s4, 0
	v_lshrrev_b32_e32 v77, 31, v76
	v_lshrrev_b32_e32 v76, 1, v76
	v_ashrrev_i32_e32 v145, 3, v143
	v_add_u32_e32 v104, v76, v77
	v_mov_b64_e32 v[76:77], s[18:19]
	v_and_b32_e32 v64, 0x70, v108
	v_mad_i64_i32 v[76:77], s[4:5], v145, s85, v[76:77]
	v_lshl_add_u64 v[136:137], v[76:77], 0, v[64:65]
	v_add_lshl_u32 v103, v75, v143, 4
	v_add_lshl_u32 v135, v104, v74, 4
	v_add_u32_e32 v141, 0, v103
	v_add_u32_e32 v140, 0, v135
	s_waitcnt vmcnt(0)
	ds_write_b128 v141, v[70:73]
	s_and_saveexec_b64 s[4:5], s[6:7]
	ds_write_b128 v140, v[160:163]
	s_or_b64 exec, exec, s[4:5]
	s_add_u32 s20, s14, 0x3000
	v_mad_u64_u32 v[104:105], s[4:5], v145, s60, v[64:65]
	s_addc_u32 s21, s15, 0
	v_add_u32_e32 v142, 0, v104
	v_lshl_add_u64 v[70:71], s[20:21], 0, v[108:109]
	s_waitcnt vmcnt(0)
	ds_write_b128 v142, v[156:159] offset:13312
	s_waitcnt lgkmcnt(0)
	s_barrier
	global_load_dwordx4 v[70:73], v[70:71], off
	s_and_saveexec_b64 s[4:5], s[6:7]
	s_cbranch_execz .LBB0_1043
	v_lshl_add_u64 v[66:67], s[20:21], 0, v[110:111]
	global_load_dwordx4 v[66:69], v[66:67], off

; __device__ __forceinline__ unsigned cvt_pk_bf16(float lo, float hi) { const f32x2c_ v = {lo, hi}; const bf16x2c_ b = __builtin_convertvector(v, bf16x2c_); return __builtin_bit_cast(unsigned, b); }
; __device__ __forceinline__ float sum32(float v) { const auto rr = __builtin_amdgcn_permlane32_swap(__float_as_uint(v), __float_as_uint(v), false, false); return __uint_as_float(rr[0]) + __uint_as_float(rr[1]); }
; #define LAS __attribute__((address_space(3)))
; __device__ __forceinline__ void attn_unit(int bh, int qb, const bf16_t* QKV, const bf16_t* KF, const float* cstab, const float* qg, bf16_t* MIX, LAS unsigned char* lds) {
;     ...
;     const int b = bh >> 3, h = bh & 7, q0 = qb * 256, qw = q0 + 32 * wid, q = qw + r32;
;     bf16x8 qf[6];
;     {
;         const bf16_t* Qp = QKV + (size_t)(b * SEQ + q) * 1792 + h * 96 + 8 * hi;
;         const float* cs = cstab + (size_t)(b * SEQ + q) * 32 + 8 * hi;
;         u32x4 raw[6];
; #pragma unroll
;         for (int d0 = 0; d0 < 6; ++d0) raw[d0] = *(const u32x4*)(Qp + 16 * d0);
;     ...
;         __syncthreads();
;     }
;     const float l = pg8::sum32(lrun), inv = 1.0f / l;
;     {
;         constexpr int OROW = 144;
;         LAS unsigned char* stg = lds + 2 * BUFB + wid * (32 * OROW);
; #pragma unroll
;         for (int rg = 0; rg < 4; ++rg) {
;             u32x2 w; w.x = cvt_pk_bf16(o0[4 * rg] * inv, o0[4 * rg + 1] * inv); w.y = cvt_pk_bf16(o0[4 * rg + 2] * inv, o0[4 * rg + 3] * inv);
;             u32x2 x; x.x = cvt_pk_bf16(o1[4 * rg] * inv, o1[4 * rg + 1] * inv); x.y = cvt_pk_bf16(o1[4 * rg + 2] * inv, o1[4 * rg + 3] * inv);
;             *(LAS u32x2*)(stg + r32 * OROW + (8 * rg + 4 * hi) * 2) = w; *(LAS u32x2*)(stg + r32 * OROW + (32 + 8 * rg + 4 * hi) * 2) = x;
;         }
;         asm volatile("s_waitcnt lgkmcnt(0)" ::: "memory");
;         bf16_t* dst = MIX + ((size_t)(b * SEQ + qw)) * 1024 + h * 64 + (lane & 7) * 8;
; #pragma unroll
;         for (int it = 0; it < 4; ++it) { const int row = it * 8 + (lane >> 3); const u32x4 v = *(const LAS u32x4*)(stg + row * OROW + (lane & 7) * 16); *(u32x4*)(dst + (size_t)row * 1024) = v; }
.LBB0_1077:
	s_add_i32 s40, s40, 1
	v_lshl_add_u64 v[112:113], v[112:113], 0, s[82:83]
	v_lshl_add_u64 v[108:109], v[108:109], 0, s[96:97]
	s_cmp_lg_u32 s42, s22
	v_lshl_add_u64 v[110:111], v[110:111], 0, s[96:97]
	s_waitcnt lgkmcnt(0)
	s_barrier
	s_cbranch_scc1 .LBB0_1057
	v_mov_b32_e32 v32, v107
	s_nop 1
	v_permlane32_swap_b32_e32 v107, v32
	v_add_f32_e32 v32, v107, v32
	v_div_scale_f32 v33, s[4:5], v32, v32, 1.0
	v_rcp_f32_e32 v34, v33
	s_mulk_i32 s39, 0x1200
	s_add_i32 s2, s39, 0
	s_add_i32 s4, s37, s28
	v_fma_f32 v35, -v33, v34, 1.0
	v_fmac_f32_e32 v34, v35, v34
	v_div_scale_f32 v35, vcc, 1.0, v32, 1.0
	v_mul_f32_e32 v36, v35, v34
	v_fma_f32 v37, -v33, v36, v35
	v_fmac_f32_e32 v36, v37, v34
	v_fma_f32 v33, -v33, v36, v35
	v_div_fmas_f32 v33, v33, v34, v36
	v_div_fixup_f32 v32, v33, v32, 1.0
	v_mul_u32_u24_e32 v33, 0x90, v138
	v_add3_u32 v33, s2, v33, v117
	v_pk_mul_f32 v[0:1], v[0:1], v[32:33] op_sel_hi:[1,0]
	v_pk_mul_f32 v[2:3], v[2:3], v[32:33] op_sel_hi:[1,0]
	v_cvt_pk_bf16_f32 v0, v0, v1
	v_cvt_pk_bf16_f32 v1, v2, v3
	v_pk_mul_f32 v[2:3], v[16:17], v[32:33] op_sel_hi:[1,0]
	v_pk_mul_f32 v[16:17], v[18:19], v[32:33] op_sel_hi:[1,0]
	v_pk_mul_f32 v[4:5], v[4:5], v[32:33] op_sel_hi:[1,0]
	v_pk_mul_f32 v[6:7], v[6:7], v[32:33] op_sel_hi:[1,0]
	v_cvt_pk_bf16_f32 v2, v2, v3
	v_cvt_pk_bf16_f32 v3, v16, v17
	v_cvt_pk_bf16_f32 v4, v4, v5
	v_cvt_pk_bf16_f32 v5, v6, v7
	v_pk_mul_f32 v[6:7], v[20:21], v[32:33] op_sel_hi:[1,0]
	v_pk_mul_f32 v[16:17], v[22:23], v[32:33] op_sel_hi:[1,0]
	v_cvt_pk_bf16_f32 v6, v6, v7
	v_cvt_pk_bf16_f32 v7, v16, v17
	v_add_u32_e32 v16, 0xc800, v33
	ds_write2_b64 v16, v[0:1], v[4:5] offset1:2
	ds_write2_b64 v16, v[2:3], v[6:7] offset0:8 offset1:10
	v_pk_mul_f32 v[0:1], v[8:9], v[32:33] op_sel_hi:[1,0]
	v_pk_mul_f32 v[2:3], v[10:11], v[32:33] op_sel_hi:[1,0]
	v_cvt_pk_bf16_f32 v0, v0, v1
	v_cvt_pk_bf16_f32 v1, v2, v3
	v_pk_mul_f32 v[2:3], v[24:25], v[32:33] op_sel_hi:[1,0]
	v_pk_mul_f32 v[4:5], v[26:27], v[32:33] op_sel_hi:[1,0]
	v_cvt_pk_bf16_f32 v2, v2, v3
	v_cvt_pk_bf16_f32 v3, v4, v5
	v_pk_mul_f32 v[4:5], v[12:13], v[32:33] op_sel_hi:[1,0]
	v_pk_mul_f32 v[6:7], v[14:15], v[32:33] op_sel_hi:[1,0]
	v_cvt_pk_bf16_f32 v4, v4, v5
	v_cvt_pk_bf16_f32 v5, v6, v7
	v_pk_mul_f32 v[6:7], v[28:29], v[32:33] op_sel_hi:[1,0]
	v_pk_mul_f32 v[8:9], v[30:31], v[32:33] op_sel_hi:[1,0]
	s_ashr_i32 s5, s4, 31
	v_cvt_pk_bf16_f32 v6, v6, v7
	v_cvt_pk_bf16_f32 v7, v8, v9
	ds_write2_b64 v16, v[0:1], v[4:5] offset0:4 offset1:6
	ds_write2_b64 v16, v[2:3], v[6:7] offset0:12 offset1:14
	s_lshl_b64 s[4:5], s[4:5], 11
	v_lshrrev_b32_e32 v4, 3, v116
	s_add_u32 s4, s16, s4
	v_mul_u32_u24_e32 v0, 0x90, v4
	s_waitcnt lgkmcnt(0)
	s_addc_u32 s5, s17, s5
	s_lshl_b32 s6, s36, 7
	v_add3_u32 v12, s2, v64, v0
	s_add_u32 s4, s4, s6
	ds_read_b128 v[0:3], v12 offset:51200
	s_addc_u32 s5, s5, 0
	v_lshl_add_u64 v[8:9], s[4:5], 0, v[64:65]
	v_lshlrev_b32_e32 v64, 11, v4
	ds_read_b128 v[4:7], v12 offset:52352
	v_lshl_add_u64 v[10:11], v[8:9], 0, v[64:65]
	s_waitcnt lgkmcnt(1)
	global_store_dwordx4 v[10:11], v[0:3], off
	v_or_b32_e32 v10, 0x8000, v64
	v_mov_b32_e32 v11, v65
	v_or_b32_e32 v0, 0x4000, v64
	v_mov_b32_e32 v1, v65
	v_lshl_add_u64 v[0:1], v[8:9], 0, v[0:1]
	s_waitcnt lgkmcnt(0)
	global_store_dwordx4 v[0:1], v[4:7], off
	ds_read_b128 v[0:3], v12 offset:53504
	ds_read_b128 v[4:7], v12 offset:54656
	v_lshl_add_u64 v[10:11], v[8:9], 0, v[10:11]
	v_or_b32_e32 v64, 0xc000, v64
	v_mov_b32_e32 v143, v228
	s_waitcnt lgkmcnt(1)
	global_store_dwordx4 v[10:11], v[0:3], off
	v_mov_b32_e32 v103, v65
	s_nop 0
	v_lshl_add_u64 v[0:1], v[8:9], 0, v[64:65]
	s_waitcnt lgkmcnt(0)
	global_store_dwordx4 v[0:1], v[4:7], off
	v_mov_b64_e32 v[2:3], s[80:81]
	v_readfirstlane_b32 s2, v143
	s_ashr_i32 s23, s2, 6
	s_lshl_b32 s2, s29, 8
	s_lshl_b32 s22, s23, 5
	v_and_b32_e32 v138, 31, v143
	s_add_i32 s22, s22, s2
	v_or_b32_e32 v139, s22, v138
	v_add_u32_e32 v0, s28, v139
	v_bfe_u32 v144, v143, 5, 1
	v_mad_i64_i32 v[2:3], s[4:5], v0, s85, v[2:3]
	v_lshl_add_u64 v[2:3], v[2:3], 0, s[78:79]
	v_lshlrev_b32_e32 v102, 4, v144
	v_lshl_add_u64 v[2:3], v[2:3], 0, v[102:103]
	global_load_dwordx4 v[32:35], v[2:3], off offset:128
	global_load_dwordx4 v[36:39], v[2:3], off offset:160
	global_load_dwordx4 v[40:43], v[2:3], off offset:96
	global_load_dwordx4 v[48:51], v[2:3], off offset:64
	global_load_dwordx4 v[56:59], v[2:3], off offset:32
	global_load_dwordx4 v[66:69], v[2:3], off
	v_ashrrev_i32_e32 v1, 31, v0
	v_lshlrev_b64 v[0:1], 7, v[0:1]
	v_lshl_add_u64 v[0:1], s[8:9], 0, v[0:1]
	v_and_b32_e32 v64, 32, v143
	v_lshl_add_u64 v[28:29], v[0:1], 0, v[64:65]
	global_load_dwordx4 v[4:7], v64, s[0:1] offset:272
	global_load_dwordx4 v[24:27], v64, s[0:1] offset:256
	global_load_dwordx4 v[8:11], v64, s[0:1] offset:336
	global_load_dwordx4 v[20:23], v64, s[0:1] offset:320
	global_load_dwordx4 v[0:3], v[28:29], off offset:16
	global_load_dwordx4 v[16:19], v[28:29], off
	global_load_dwordx4 v[12:15], v[28:29], off offset:80
	s_nop 0
	global_load_dwordx4 v[28:31], v[28:29], off offset:64
	v_lshlrev_b32_e32 v108, 4, v143
	v_ashrrev_i32_e32 v109, 31, v108
	v_add_u32_e32 v74, 0x200, v143
	s_movk_i32 s2, 0x100
	v_lshlrev_b32_e32 v110, 4, v74
	v_cmp_gt_i32_e64 s[6:7], s2, v143
	v_ashrrev_i32_e32 v111, 31, v110
	s_waitcnt vmcnt(13)
	v_lshlrev_b32_e32 v94, 16, v35
	v_and_b32_e32 v95, 0xffff0000, v35
	s_waitcnt vmcnt(12)
	v_lshlrev_b32_e32 v96, 16, v39
	v_and_b32_e32 v97, 0xffff0000, v39
	v_lshlrev_b32_e32 v98, 16, v34
	s_waitcnt vmcnt(8)
; __device__ __forceinline__ float sum32(float v) { const auto rr = __builtin_amdgcn_permlane32_swap(__float_as_uint(v), __float_as_uint(v), false, false); return __uint_as_float(rr[0]) + __uint_as_float(rr[1]); }
; __device__ __forceinline__ u32x4 pack8(const float* v) { u32x4 w; w.x = cvt_pk_bf16(v[0], v[1]); w.y = cvt_pk_bf16(v[2], v[3]); w.z = cvt_pk_bf16(v[4], v[5]); w.w = cvt_pk_bf16(v[6], v[7]); return w; }
; __device__ __forceinline__ void attn_unit(int bh, int qb, const bf16_t* QKV, const bf16_t* KF, const float* cstab, const float* qg, bf16_t* MIX, LAS unsigned char* lds) {
;     ...
;         for (int d0 = 0; d0 < 6; ++d0) raw[d0] = *(const u32x4*)(Qp + 16 * d0);
;         float ss = 0.f;
; #pragma unroll
;         for (int d0 = 0; d0 < 6; ++d0) { float v[8]; unpack8(raw[d0], v);
; #pragma unroll
;             for (int i = 0; i < 8; ++i) ss += v[i] * v[i]; }
;         ss = pg8::sum32(ss);
;         const float rs = __builtin_amdgcn_rsqf(ss * (1.0f / 96.0f) + EPS) * C2Q;
; #pragma unroll
;         for (int d0 = 0; d0 < 4; ++d0) { float v[8]; unpack8(raw[d0], v);
; #pragma unroll
;             for (int i = 0; i < 8; ++i) v[i] = v[i] * rs * qg[16 * d0 + 8 * hi + i];
;             qf[d0] = __builtin_bit_cast(bf16x8, pack8(v)); }
;         float x1[8], x2[8], o1[8], o2[8]; unpack8(raw[4], x1); unpack8(raw[5], x2);
; #pragma unroll
;         for (int i = 0; i < 8; ++i) { const float y1 = x1[i] * rs * qg[64 + 8 * hi + i], y2 = x2[i] * rs * qg[80 + 8 * hi + i], co = cs[i], si = cs[16 + i];
;             o1[i] = y1 * co - y2 * si; o2[i] = y1 * si + y2 * co; }
;         qf[4] = __builtin_bit_cast(bf16x8, pack8(o1)); qf[5] = __builtin_bit_cast(bf16x8, pack8(o2));
;     }
;     const char* Kg = (const char*)(KF + (size_t)bh * SEQ * 96);
;     const char* Vg = (const char*)(QKV + (size_t)b * SEQ * 1792 + 768 + h * 128 + 64) + (size_t)(tid >> 3) * 3584 + (tid & 7) * 16;
;     const int kofs0 = (tid / 12) * KROW + (tid % 12) * 16, kofs1 = ((tid + 512) / 12) * KROW + ((tid + 512) % 12) * 16, vofs = KBUF + (tid >> 3) * VROW + (tid & 7) * 16;
;     const int vtb = KBUF + (4 * hi + ((lane & 15) >> 2)) * VROW + (16 * ((lane >> 4) & 1) + 4 * (lane & 3)) * 2;
;     const int NT = 4 * (qb + 1);
;     u32x4 kr0, kr1 = {0u, 0u, 0u, 0u}, vr;
	v_lshlrev_b32_e32 v126, 16, v69
	v_and_b32_e32 v127, 0xffff0000, v69
	v_lshlrev_b32_e32 v128, 16, v68
	v_and_b32_e32 v129, 0xffff0000, v68
	v_lshl_add_u64 v[68:69], s[14:15], 0, v[108:109]
	v_and_b32_e32 v99, 0xffff0000, v34
	v_lshlrev_b32_e32 v100, 16, v38
	v_and_b32_e32 v101, 0xffff0000, v38
	v_lshlrev_b32_e32 v106, 16, v33
	v_and_b32_e32 v107, 0xffff0000, v33
	v_lshlrev_b32_e32 v112, 16, v37
	v_and_b32_e32 v113, 0xffff0000, v37
	v_lshlrev_b32_e32 v114, 16, v32
	v_and_b32_e32 v115, 0xffff0000, v32
	v_lshlrev_b32_e32 v116, 16, v36
	v_and_b32_e32 v117, 0xffff0000, v36
	v_lshlrev_b32_e32 v90, 16, v43
	v_and_b32_e32 v91, 0xffff0000, v43
	global_load_dwordx4 v[32:35], v64, s[0:1] offset:208
	global_load_dwordx4 v[36:39], v64, s[0:1] offset:192
	v_lshlrev_b32_e32 v92, 16, v42
	v_and_b32_e32 v93, 0xffff0000, v42
	v_lshlrev_b32_e32 v118, 16, v41
	v_and_b32_e32 v119, 0xffff0000, v41
	v_lshlrev_b32_e32 v120, 16, v40
	v_and_b32_e32 v121, 0xffff0000, v40
	v_lshlrev_b32_e32 v82, 16, v51
	v_and_b32_e32 v83, 0xffff0000, v51
	global_load_dwordx4 v[40:43], v64, s[0:1] offset:144
	global_load_dwordx4 v[44:47], v64, s[0:1] offset:128
	v_lshlrev_b32_e32 v84, 16, v50
	v_and_b32_e32 v85, 0xffff0000, v50
	v_lshlrev_b32_e32 v122, 16, v49
	v_and_b32_e32 v123, 0xffff0000, v49
	v_lshlrev_b32_e32 v124, 16, v48
	v_and_b32_e32 v125, 0xffff0000, v48
	v_lshlrev_b32_e32 v78, 16, v59
	v_and_b32_e32 v79, 0xffff0000, v59
	global_load_dwordx4 v[48:51], v64, s[0:1] offset:80
	global_load_dwordx4 v[52:55], v64, s[0:1] offset:64
	v_lshlrev_b32_e32 v80, 16, v58
	v_and_b32_e32 v81, 0xffff0000, v58
	v_lshlrev_b32_e32 v86, 16, v57
	v_and_b32_e32 v87, 0xffff0000, v57
	v_lshlrev_b32_e32 v88, 16, v56
	v_and_b32_e32 v89, 0xffff0000, v56
	global_load_dwordx4 v[56:59], v64, s[0:1] offset:16
	global_load_dwordx4 v[60:63], v64, s[0:1]
	global_load_dwordx4 v[70:73], v[68:69], off
	v_mov_b64_e32 v[166:167], s[18:19]
	v_ashrrev_i32_e32 v164, 3, v143
	s_nop 0
	v_mad_i64_i32 v[166:167], s[100:101], v164, s85, v[166:167]
	v_and_b32_e32 v164, 0x70, v108
	v_mov_b32_e32 v165, 0
	v_lshl_add_u64 v[166:167], v[166:167], 0, v[164:165]
	global_load_dwordx4 v[156:159], v[166:167], off offset:1664
	v_add_u32_e32 v168, 0x200, v143
	v_lshlrev_b32_e32 v168, 4, v168
	v_mov_b32_e32 v169, 0
	v_lshl_add_u64 v[168:169], s[14:15], 0, v[168:169]
	s_and_saveexec_b64 s[100:101], s[6:7]
	global_load_dwordx4 v[160:163], v[168:169], off
	s_mov_b64 exec, s[100:101]
	v_and_b32_e32 v133, 0xffff0000, v66
	v_lshlrev_b32_e32 v132, 16, v66
	v_mul_f32_e32 v64, v133, v133
	v_lshlrev_b32_e32 v130, 16, v67
	v_and_b32_e32 v131, 0xffff0000, v67
	v_pk_fma_f32 v[66:67], v[132:133], v[132:133], v[64:65] op_sel_hi:[1,1,0]
	v_mul_f32_e32 v64, v131, v131
	v_pk_fma_f32 v[66:67], v[130:131], v[130:131], v[66:67]
	s_nop 0
	v_pk_add_f32 v[66:67], v[64:65], v[66:67] op_sel_hi:[0,1]
	v_pk_fma_f32 v[66:67], v[128:129], v[128:129], v[66:67]
	v_mul_f32_e32 v64, v129, v129
	v_pk_add_f32 v[66:67], v[64:65], v[66:67] op_sel_hi:[0,1]
	v_pk_fma_f32 v[66:67], v[126:127], v[126:127], v[66:67]
	v_mul_f32_e32 v64, v127, v127
	v_pk_add_f32 v[66:67], v[64:65], v[66:67] op_sel_hi:[0,1]
	v_pk_fma_f32 v[66:67], v[88:89], v[88:89], v[66:67]
	v_mul_f32_e32 v64, v89, v89
	v_pk_add_f32 v[66:67], v[64:65], v[66:67] op_sel_hi:[0,1]
	v_pk_fma_f32 v[66:67], v[86:87], v[86:87], v[66:67]
	v_mul_f32_e32 v64, v87, v87
	v_pk_add_f32 v[66:67], v[64:65], v[66:67] op_sel_hi:[0,1]
	v_pk_fma_f32 v[66:67], v[80:81], v[80:81], v[66:67]
	v_mul_f32_e32 v64, v81, v81
	v_pk_add_f32 v[66:67], v[64:65], v[66:67] op_sel_hi:[0,1]
	v_pk_fma_f32 v[66:67], v[78:79], v[78:79], v[66:67]
	v_mul_f32_e32 v64, v79, v79
	v_pk_add_f32 v[66:67], v[64:65], v[66:67] op_sel_hi:[0,1]
	v_pk_fma_f32 v[66:67], v[124:125], v[124:125], v[66:67]
	v_mul_f32_e32 v64, v125, v125
	v_pk_add_f32 v[66:67], v[64:65], v[66:67] op_sel_hi:[0,1]
	v_pk_fma_f32 v[66:67], v[122:123], v[122:123], v[66:67]
	v_mul_f32_e32 v64, v123, v123
	v_pk_add_f32 v[66:67], v[64:65], v[66:67] op_sel_hi:[0,1]
	v_pk_fma_f32 v[66:67], v[84:85], v[84:85], v[66:67]
	v_mul_f32_e32 v64, v85, v85
	v_pk_add_f32 v[66:67], v[64:65], v[66:67] op_sel_hi:[0,1]
	v_pk_fma_f32 v[66:67], v[82:83], v[82:83], v[66:67]
	v_mul_f32_e32 v64, v83, v83
	v_pk_add_f32 v[66:67], v[64:65], v[66:67] op_sel_hi:[0,1]
	v_pk_fma_f32 v[66:67], v[120:121], v[120:121], v[66:67]
	v_mul_f32_e32 v64, v121, v121
	v_pk_add_f32 v[66:67], v[64:65], v[66:67] op_sel_hi:[0,1]
	v_pk_fma_f32 v[66:67], v[118:119], v[118:119], v[66:67]
	v_mul_f32_e32 v64, v119, v119
	v_pk_add_f32 v[66:67], v[64:65], v[66:67] op_sel_hi:[0,1]
	v_pk_fma_f32 v[66:67], v[92:93], v[92:93], v[66:67]
	v_mul_f32_e32 v64, v93, v93
	v_pk_add_f32 v[66:67], v[64:65], v[66:67] op_sel_hi:[0,1]
	v_pk_fma_f32 v[66:67], v[90:91], v[90:91], v[66:67]
	v_mul_f32_e32 v64, v91, v91
	v_pk_add_f32 v[66:67], v[64:65], v[66:67] op_sel_hi:[0,1]
	v_pk_fma_f32 v[66:67], v[114:115], v[114:115], v[66:67]
	v_mul_f32_e32 v64, v115, v115
	v_pk_add_f32 v[66:67], v[64:65], v[66:67] op_sel_hi:[0,1]
	v_pk_fma_f32 v[66:67], v[106:107], v[106:107], v[66:67]
	v_mul_f32_e32 v64, v107, v107
	v_pk_add_f32 v[66:67], v[64:65], v[66:67] op_sel_hi:[0,1]
	v_pk_fma_f32 v[66:67], v[98:99], v[98:99], v[66:67]
	v_mul_f32_e32 v64, v99, v99
	v_pk_add_f32 v[66:67], v[64:65], v[66:67] op_sel_hi:[0,1]
	v_pk_fma_f32 v[66:67], v[94:95], v[94:95], v[66:67]
	v_mul_f32_e32 v64, v95, v95
	v_pk_add_f32 v[66:67], v[64:65], v[66:67] op_sel_hi:[0,1]
	v_pk_fma_f32 v[66:67], v[116:117], v[116:117], v[66:67]
	v_mul_f32_e32 v64, v117, v117
	v_pk_add_f32 v[66:67], v[64:65], v[66:67] op_sel_hi:[0,1]
	v_pk_fma_f32 v[66:67], v[112:113], v[112:113], v[66:67]
	v_mul_f32_e32 v64, v113, v113
	v_pk_add_f32 v[66:67], v[64:65], v[66:67] op_sel_hi:[0,1]
	v_pk_fma_f32 v[66:67], v[100:101], v[100:101], v[66:67]
	v_mul_f32_e32 v64, v101, v101
	v_pk_add_f32 v[66:67], v[64:65], v[66:67] op_sel_hi:[0,1]
	v_pk_fma_f32 v[66:67], v[96:97], v[96:97], v[66:67]
	v_mul_f32_e32 v64, v97, v97
	v_pk_add_f32 v[134:135], v[64:65], v[66:67] op_sel_hi:[0,1]
	v_mov_b32_e32 v66, v65
	v_mov_b32_e32 v67, v65
	v_mov_b32_e32 v146, v134
	v_mov_b32_e32 v64, v65
	v_mov_b64_e32 v[68:69], v[66:67]
	v_permlane32_swap_b32_e32 v134, v146
	v_mov_b64_e32 v[66:67], v[64:65]
	s_and_saveexec_b64 s[4:5], s[6:7]
	s_cbranch_execz .LBB0_1080
	v_lshl_add_u64 v[66:67], s[14:15], 0, v[110:111]
; #define LAS __attribute__((address_space(3)))
; #define ATT_LOAD(t) do { kr0 = *(const u32x4*)(Kg + (size_t)(t) * 12288 + tid * 16); if (tid < 256) kr1 = *(const u32x4*)(Kg + (size_t)(t) * 12288 + (tid + 512) * 16); vr = *(const u32x4*)(Vg + (size_t)(t) * (64 * 3584)); } while (0)
; #define ATT_WRITE(bufp) do { *(LAS u32x4*)((bufp) + kofs0) = kr0; if (tid < 256) *(LAS u32x4*)((bufp) + kofs1) = kr1; *(LAS u32x4*)((bufp) + vofs) = vr; } while (0)
; __device__ __forceinline__ void attn_unit(int bh, int qb, const bf16_t* QKV, const bf16_t* KF, const float* cstab, const float* qg, bf16_t* MIX, LAS unsigned char* lds) {
;     ...
;     const int kofs0 = (tid / 12) * KROW + (tid % 12) * 16, kofs1 = ((tid + 512) / 12) * KROW + ((tid + 512) % 12) * 16, vofs = KBUF + (tid >> 3) * VROW + (tid & 7) * 16;
;     const int vtb = KBUF + (4 * hi + ((lane & 15) >> 2)) * VROW + (16 * ((lane >> 4) & 1) + 4 * (lane & 3)) * 2;
;     const int NT = 4 * (qb + 1);
;     u32x4 kr0, kr1 = {0u, 0u, 0u, 0u}, vr;
;     ...
;     float mrun = 0.f, lrun = 0.f;
;     f32x16 o0, o1, negm;
; #pragma unroll
;     for (int r = 0; r < 16; ++r) { o0[r] = 0.f; o1[r] = 0.f; negm[r] = 0.f; }
;     ATT_LOAD(0); ATT_WRITE(lds);
;     __syncthreads();
;     for (int t = 0; t < NT; ++t) {
;         LAS unsigned char* buf = lds + (t & 1) * BUFB;
;         if (t + 1 < NT) ATT_LOAD(t + 1);
.LBB0_1080:
	s_or_b64 exec, exec, s[4:5]
	s_mov_b32 s2, 0x2aaaaaab
	v_mul_hi_i32 v75, v143, s2
	v_lshrrev_b32_e32 v76, 31, v75
	v_lshrrev_b32_e32 v75, 1, v75
	v_add_u32_e32 v75, v75, v76
	v_mul_hi_i32 v76, v74, s2
	v_lshrrev_b32_e32 v77, 31, v76
	v_lshrrev_b32_e32 v76, 1, v76
	v_ashrrev_i32_e32 v145, 3, v143
	v_add_u32_e32 v104, v76, v77
	v_mov_b64_e32 v[76:77], s[18:19]
	v_and_b32_e32 v64, 0x70, v108
	v_mad_i64_i32 v[76:77], s[4:5], v145, s85, v[76:77]
	v_lshl_add_u64 v[136:137], v[76:77], 0, v[64:65]
	v_add_lshl_u32 v103, v75, v143, 4
	v_add_lshl_u32 v135, v104, v74, 4
	v_add_u32_e32 v142, 0, v103
	v_add_u32_e32 v140, 0, v135
	s_waitcnt vmcnt(0)
	ds_write_b128 v142, v[70:73]
	s_and_saveexec_b64 s[4:5], s[6:7]
	ds_write_b128 v140, v[160:163]
	s_or_b64 exec, exec, s[4:5]
	v_mad_u64_u32 v[104:105], s[4:5], v145, s46, v[64:65]
	v_add_u32_e32 v141, 0, v104
	v_lshl_add_u64 v[70:71], s[20:21], 0, v[108:109]
	s_waitcnt vmcnt(0)
	ds_write_b128 v141, v[156:159] offset:13312
	s_waitcnt lgkmcnt(0)
	s_barrier
	global_load_dwordx4 v[70:73], v[70:71], off
	s_and_saveexec_b64 s[4:5], s[6:7]
	s_cbranch_execz .LBB0_1084
	v_lshl_add_u64 v[66:67], s[20:21], 0, v[110:111]
	global_load_dwordx4 v[66:69], v[66:67], off
